# strategy #2 (epilogue de-serialisation): v42 + P6 epilogue reads all 8 per-row-group rstd values from LDS at once after the exchange barrier (was ds_read_b32 + lgkmcnt(0) eight times per unit)
# speedup vs baseline: 1.0007x; 1.0007x over previous
.LBB0_1119:
	s_or_b64 exec, exec, s[8:9]
	s_add_i32 s11, s11, s46
	s_waitcnt vmcnt(0)
	v_bfe_u32 v117, v150, 2, 4
	v_or_b32_e32 v121, s11, v117
	s_lshl_b32 s8, s12, 7
	v_lshlrev_b32_e32 v117, 3, v149
	v_and_or_b32 v117, v117, 24, s8
	v_and_b32_e32 v116, 63, v150
	v_or_b32_e32 v118, s47, v117
	v_lshlrev_b32_e32 v117, 6, v149
	s_movk_i32 s8, 0xfc
	v_bitop3_b32 v120, v117, s8, v116 bitop3:0xc8
	v_readlane_b32 s8, v255, 5
	v_readlane_b32 s9, v255, 6
	v_ashrrev_i32_e32 v119, 31, v118
	s_movk_i32 s11, 0x2c00
	v_mov_b64_e32 v[116:117], s[8:9]
	v_mad_i64_i32 v[122:123], s[8:9], v121, s11, v[116:117]
	v_lshlrev_b64 v[118:119], 1, v[118:119]
	s_waitcnt lgkmcnt(0)
	s_barrier
	v_lshl_add_u64 v[150:151], v[122:123], 0, v[118:119]
	v_lshl_add_u32 v122, v149, 2, s51
	ds_read_b32 v236, v122
	ds_read_b32 v237, v122 offset:64
	ds_read_b32 v238, v122 offset:128
	ds_read_b32 v239, v122 offset:192
	ds_read_b32 v240, v122 offset:512
	ds_read_b32 v241, v122 offset:576
	ds_read_b32 v242, v122 offset:640
	ds_read_b32 v243, v122 offset:704
	v_pk_mul_f32 v[130:131], v[126:127], v[130:131]
	v_pk_mul_f32 v[138:139], v[134:135], v[138:139]
	v_pk_mul_f32 v[136:137], v[132:133], v[136:137]
	v_pk_mul_f32 v[128:129], v[124:125], v[128:129]
	s_waitcnt lgkmcnt(0)
	v_mov_b32_e32 v123, v236
	v_mul_f32_e32 v152, 0xbfb8aa3b, v123
	v_pk_mul_f32 v[126:127], v[126:127], v[152:153] op_sel_hi:[1,0]
	v_pk_mul_f32 v[132:133], v[132:133], v[152:153] op_sel_hi:[1,0]
	v_pk_mul_f32 v[134:135], v[134:135], v[152:153] op_sel_hi:[1,0]
	v_pk_mul_f32 v[124:125], v[124:125], v[152:153] op_sel_hi:[1,0]
	v_exp_f32_e32 v126, v126
	v_exp_f32_e32 v127, v127
	v_exp_f32_e32 v132, v132
	v_exp_f32_e32 v133, v133
	v_exp_f32_e32 v134, v134
	v_exp_f32_e32 v135, v135
	v_exp_f32_e32 v124, v124
	v_exp_f32_e32 v125, v125
	v_pk_add_f32 v[126:127], v[126:127], 1.0 op_sel_hi:[1,0]
	v_pk_add_f32 v[132:133], v[132:133], 1.0 op_sel_hi:[1,0]
	v_pk_add_f32 v[134:135], v[134:135], 1.0 op_sel_hi:[1,0]
	v_pk_add_f32 v[124:125], v[124:125], 1.0 op_sel_hi:[1,0]
	v_rcp_f32_e32 v126, v126
	v_rcp_f32_e32 v127, v127
	v_rcp_f32_e32 v132, v132
	v_rcp_f32_e32 v133, v133
	v_rcp_f32_e32 v134, v134
	v_rcp_f32_e32 v135, v135
	v_rcp_f32_e32 v124, v124
	v_rcp_f32_e32 v125, v125
	v_mul_f32_e32 v154, v123, v123
	v_pk_mul_f32 v[126:127], v[154:155], v[126:127] op_sel_hi:[0,1]
	v_pk_mul_f32 v[132:133], v[154:155], v[132:133] op_sel_hi:[0,1]
	v_pk_mul_f32 v[134:135], v[154:155], v[134:135] op_sel_hi:[0,1]
	v_pk_mul_f32 v[124:125], v[154:155], v[124:125] op_sel_hi:[0,1]
	v_pk_mul_f32 v[126:127], v[130:131], v[126:127]
	v_pk_mul_f32 v[132:133], v[136:137], v[132:133]
	v_pk_mul_f32 v[134:135], v[138:139], v[134:135]
	v_pk_mul_f32 v[124:125], v[128:129], v[124:125]
	v_cvt_pk_bf16_f32 v123, v132, v133
	v_cvt_pk_bf16_f32 v128, v134, v135
	v_pk_mul_f32 v[106:107], v[102:103], v[106:107]
	v_cvt_pk_bf16_f32 v129, v124, v125
	v_cvt_pk_bf16_f32 v127, v126, v127
	ds_bpermute_b32 v124, v120, v123
	ds_bpermute_b32 v125, v120, v128
	ds_bpermute_b32 v126, v120, v129
	ds_bpermute_b32 v127, v120, v127
	v_or_b32_e32 v123, 16, v121
	v_pk_mul_f32 v[114:115], v[110:111], v[114:115]
	v_pk_mul_f32 v[112:113], v[108:109], v[112:113]
	v_pk_mul_f32 v[104:105], v[100:101], v[104:105]
	s_waitcnt lgkmcnt(0)
	global_store_dwordx4 v[150:151], v[124:127], off
	v_pk_mul_f32 v[90:91], v[86:87], v[90:91]
	v_pk_mul_f32 v[98:99], v[94:95], v[98:99]
	v_mad_i64_i32 v[124:125], s[8:9], v123, s11, v[116:117]
	s_nop 1
	v_mov_b32_e32 v123, v237
	v_lshl_add_u64 v[124:125], v[124:125], 0, v[118:119]
	v_pk_mul_f32 v[96:97], v[92:93], v[96:97]
	v_pk_mul_f32 v[88:89], v[84:85], v[88:89]
	v_pk_mul_f32 v[74:75], v[70:71], v[74:75]
	s_waitcnt lgkmcnt(0)
	v_mul_f32_e32 v126, 0xbfb8aa3b, v123
	v_pk_mul_f32 v[102:103], v[102:103], v[126:127] op_sel_hi:[1,0]
	v_pk_mul_f32 v[108:109], v[108:109], v[126:127] op_sel_hi:[1,0]
	v_pk_mul_f32 v[110:111], v[110:111], v[126:127] op_sel_hi:[1,0]
	v_pk_mul_f32 v[100:101], v[100:101], v[126:127] op_sel_hi:[1,0]
	v_exp_f32_e32 v102, v102
	v_exp_f32_e32 v103, v103
	v_exp_f32_e32 v108, v108
	v_exp_f32_e32 v109, v109
	v_exp_f32_e32 v110, v110
	v_exp_f32_e32 v111, v111
	v_exp_f32_e32 v100, v100
	v_exp_f32_e32 v101, v101
	v_pk_add_f32 v[102:103], v[102:103], 1.0 op_sel_hi:[1,0]
	v_pk_add_f32 v[108:109], v[108:109], 1.0 op_sel_hi:[1,0]
	v_pk_add_f32 v[110:111], v[110:111], 1.0 op_sel_hi:[1,0]
	v_pk_add_f32 v[100:101], v[100:101], 1.0 op_sel_hi:[1,0]
	v_rcp_f32_e32 v102, v102
	v_rcp_f32_e32 v103, v103
	v_rcp_f32_e32 v108, v108
	v_rcp_f32_e32 v109, v109
	v_rcp_f32_e32 v110, v110
	v_rcp_f32_e32 v111, v111
	v_rcp_f32_e32 v100, v100
	v_rcp_f32_e32 v101, v101
	v_mul_f32_e32 v128, v123, v123
	v_pk_mul_f32 v[102:103], v[128:129], v[102:103] op_sel_hi:[0,1]
	v_pk_mul_f32 v[108:109], v[128:129], v[108:109] op_sel_hi:[0,1]
	v_pk_mul_f32 v[110:111], v[128:129], v[110:111] op_sel_hi:[0,1]
	v_pk_mul_f32 v[100:101], v[128:129], v[100:101] op_sel_hi:[0,1]
	v_pk_mul_f32 v[102:103], v[106:107], v[102:103]
	v_pk_mul_f32 v[108:109], v[112:113], v[108:109]
	v_pk_mul_f32 v[110:111], v[114:115], v[110:111]
	v_pk_mul_f32 v[100:101], v[104:105], v[100:101]
	v_cvt_pk_bf16_f32 v104, v108, v109
	v_cvt_pk_bf16_f32 v105, v110, v111
	v_pk_mul_f32 v[82:83], v[78:79], v[82:83]
	v_cvt_pk_bf16_f32 v106, v100, v101
	v_cvt_pk_bf16_f32 v103, v102, v103
	ds_bpermute_b32 v100, v120, v104
	ds_bpermute_b32 v101, v120, v105
	ds_bpermute_b32 v102, v120, v106
	ds_bpermute_b32 v103, v120, v103
	v_pk_mul_f32 v[80:81], v[76:77], v[80:81]
	v_pk_mul_f32 v[72:73], v[68:69], v[72:73]
	v_pk_mul_f32 v[58:59], v[54:55], v[58:59]
	v_pk_mul_f32 v[66:67], v[62:63], v[66:67]
	s_waitcnt lgkmcnt(0)
	global_store_dwordx4 v[124:125], v[100:103], off
	s_nop 1
	v_mov_b32_e32 v103, v238
	v_pk_mul_f32 v[64:65], v[60:61], v[64:65]
	v_or_b32_e32 v100, 32, v121
	v_mad_i64_i32 v[100:101], s[8:9], v100, s11, v[116:117]
	s_waitcnt lgkmcnt(0)
	v_mul_f32_e32 v102, 0xbfb8aa3b, v103
	v_pk_mul_f32 v[86:87], v[86:87], v[102:103] op_sel_hi:[1,0]
	v_pk_mul_f32 v[92:93], v[92:93], v[102:103] op_sel_hi:[1,0]
	v_pk_mul_f32 v[94:95], v[94:95], v[102:103] op_sel_hi:[1,0]
	v_pk_mul_f32 v[84:85], v[84:85], v[102:103] op_sel_hi:[1,0]
	v_exp_f32_e32 v86, v86
	v_exp_f32_e32 v87, v87
	v_exp_f32_e32 v92, v92
	v_exp_f32_e32 v93, v93
	v_exp_f32_e32 v94, v94
	v_exp_f32_e32 v95, v95
	v_exp_f32_e32 v84, v84
	v_exp_f32_e32 v85, v85
	v_pk_add_f32 v[86:87], v[86:87], 1.0 op_sel_hi:[1,0]
	v_pk_add_f32 v[92:93], v[92:93], 1.0 op_sel_hi:[1,0]
	v_pk_add_f32 v[94:95], v[94:95], 1.0 op_sel_hi:[1,0]
	v_pk_add_f32 v[84:85], v[84:85], 1.0 op_sel_hi:[1,0]
	v_rcp_f32_e32 v86, v86
	v_rcp_f32_e32 v87, v87
	v_rcp_f32_e32 v92, v92
	v_rcp_f32_e32 v93, v93
	v_rcp_f32_e32 v94, v94
	v_rcp_f32_e32 v95, v95
	v_rcp_f32_e32 v84, v84
	v_rcp_f32_e32 v85, v85
	v_mul_f32_e32 v104, v103, v103
	v_pk_mul_f32 v[86:87], v[104:105], v[86:87] op_sel_hi:[0,1]
	v_pk_mul_f32 v[92:93], v[104:105], v[92:93] op_sel_hi:[0,1]
	v_pk_mul_f32 v[94:95], v[104:105], v[94:95] op_sel_hi:[0,1]
	v_pk_mul_f32 v[84:85], v[104:105], v[84:85] op_sel_hi:[0,1]
	v_pk_mul_f32 v[86:87], v[90:91], v[86:87]
	v_pk_mul_f32 v[92:93], v[96:97], v[92:93]
	v_pk_mul_f32 v[94:95], v[98:99], v[94:95]
	v_pk_mul_f32 v[84:85], v[88:89], v[84:85]
	v_cvt_pk_bf16_f32 v88, v92, v93
	v_cvt_pk_bf16_f32 v89, v94, v95
	v_lshl_add_u64 v[100:101], v[100:101], 0, v[118:119]
	v_cvt_pk_bf16_f32 v90, v84, v85
	v_cvt_pk_bf16_f32 v87, v86, v87
	ds_bpermute_b32 v84, v120, v88
	ds_bpermute_b32 v85, v120, v89
	ds_bpermute_b32 v86, v120, v90
	ds_bpermute_b32 v87, v120, v87
	v_pk_mul_f32 v[56:57], v[52:53], v[56:57]
	v_pk_mul_f32 v[42:43], v[38:39], v[42:43]
	v_pk_mul_f32 v[50:51], v[46:47], v[50:51]
	v_pk_mul_f32 v[48:49], v[44:45], v[48:49]
	s_waitcnt lgkmcnt(0)
	global_store_dwordx4 v[100:101], v[84:87], off
	s_nop 1
	v_mov_b32_e32 v87, v239
	v_pk_mul_f32 v[40:41], v[36:37], v[40:41]
	v_or_b32_e32 v84, 48, v121
	v_mad_i64_i32 v[84:85], s[8:9], v84, s11, v[116:117]
	s_waitcnt lgkmcnt(0)
	v_mul_f32_e32 v86, 0xbfb8aa3b, v87
	v_pk_mul_f32 v[70:71], v[70:71], v[86:87] op_sel_hi:[1,0]
	v_pk_mul_f32 v[76:77], v[76:77], v[86:87] op_sel_hi:[1,0]
	v_pk_mul_f32 v[78:79], v[78:79], v[86:87] op_sel_hi:[1,0]
	v_pk_mul_f32 v[68:69], v[68:69], v[86:87] op_sel_hi:[1,0]
	v_exp_f32_e32 v70, v70
	v_exp_f32_e32 v71, v71
	v_exp_f32_e32 v76, v76
	v_exp_f32_e32 v77, v77
	v_exp_f32_e32 v78, v78
	v_exp_f32_e32 v79, v79
	v_exp_f32_e32 v68, v68
	v_exp_f32_e32 v69, v69
	v_pk_add_f32 v[70:71], v[70:71], 1.0 op_sel_hi:[1,0]
	v_pk_add_f32 v[76:77], v[76:77], 1.0 op_sel_hi:[1,0]
	v_pk_add_f32 v[78:79], v[78:79], 1.0 op_sel_hi:[1,0]
	v_pk_add_f32 v[68:69], v[68:69], 1.0 op_sel_hi:[1,0]
	v_rcp_f32_e32 v70, v70
	v_rcp_f32_e32 v71, v71
	v_rcp_f32_e32 v76, v76
	v_rcp_f32_e32 v77, v77
	v_rcp_f32_e32 v78, v78
	v_rcp_f32_e32 v79, v79
	v_rcp_f32_e32 v68, v68
	v_rcp_f32_e32 v69, v69
	v_mul_f32_e32 v88, v87, v87
	v_pk_mul_f32 v[70:71], v[88:89], v[70:71] op_sel_hi:[0,1]
	v_pk_mul_f32 v[76:77], v[88:89], v[76:77] op_sel_hi:[0,1]
	v_pk_mul_f32 v[78:79], v[88:89], v[78:79] op_sel_hi:[0,1]
	v_pk_mul_f32 v[68:69], v[88:89], v[68:69] op_sel_hi:[0,1]
	v_pk_mul_f32 v[70:71], v[74:75], v[70:71]
	v_pk_mul_f32 v[76:77], v[80:81], v[76:77]
	v_pk_mul_f32 v[78:79], v[82:83], v[78:79]
	v_pk_mul_f32 v[68:69], v[72:73], v[68:69]
	v_cvt_pk_bf16_f32 v72, v76, v77
	v_cvt_pk_bf16_f32 v73, v78, v79
	v_lshl_add_u64 v[84:85], v[84:85], 0, v[118:119]
	v_cvt_pk_bf16_f32 v74, v68, v69
	v_cvt_pk_bf16_f32 v71, v70, v71
	ds_bpermute_b32 v68, v120, v72
	ds_bpermute_b32 v69, v120, v73
	ds_bpermute_b32 v70, v120, v74
	ds_bpermute_b32 v71, v120, v71
	v_pk_mul_f32 v[24:25], v[20:21], v[24:25]
	v_pk_mul_f32 v[32:33], v[28:29], v[32:33]
	v_pk_mul_f32 v[30:31], v[26:27], v[30:31]
	v_pk_mul_f32 v[22:23], v[18:19], v[22:23]
	s_waitcnt lgkmcnt(0)
	global_store_dwordx4 v[84:85], v[68:71], off
	s_nop 1
	v_mov_b32_e32 v71, v240
	v_pk_mul_f32 v[2:3], v[6:7], v[2:3]
	v_add_u32_e32 v68, 0x80, v121
	v_mad_i64_i32 v[68:69], s[8:9], v68, s11, v[116:117]
	s_waitcnt lgkmcnt(0)
	v_mul_f32_e32 v70, 0xbfb8aa3b, v71
	v_pk_mul_f32 v[54:55], v[54:55], v[70:71] op_sel_hi:[1,0]
	v_pk_mul_f32 v[60:61], v[60:61], v[70:71] op_sel_hi:[1,0]
	v_pk_mul_f32 v[62:63], v[62:63], v[70:71] op_sel_hi:[1,0]
	v_pk_mul_f32 v[52:53], v[52:53], v[70:71] op_sel_hi:[1,0]
	v_exp_f32_e32 v54, v54
	v_exp_f32_e32 v55, v55
	v_exp_f32_e32 v60, v60
	v_exp_f32_e32 v61, v61
	v_exp_f32_e32 v62, v62
	v_exp_f32_e32 v63, v63
	v_exp_f32_e32 v52, v52
	v_exp_f32_e32 v53, v53
	v_pk_add_f32 v[54:55], v[54:55], 1.0 op_sel_hi:[1,0]
	v_pk_add_f32 v[60:61], v[60:61], 1.0 op_sel_hi:[1,0]
	v_pk_add_f32 v[62:63], v[62:63], 1.0 op_sel_hi:[1,0]
	v_pk_add_f32 v[52:53], v[52:53], 1.0 op_sel_hi:[1,0]
	v_rcp_f32_e32 v54, v54
	v_rcp_f32_e32 v55, v55
	v_rcp_f32_e32 v60, v60
	v_rcp_f32_e32 v61, v61
	v_rcp_f32_e32 v62, v62
	v_rcp_f32_e32 v63, v63
	v_rcp_f32_e32 v52, v52
	v_rcp_f32_e32 v53, v53
	v_mul_f32_e32 v72, v71, v71
	v_pk_mul_f32 v[54:55], v[72:73], v[54:55] op_sel_hi:[0,1]
	v_pk_mul_f32 v[60:61], v[72:73], v[60:61] op_sel_hi:[0,1]
	v_pk_mul_f32 v[62:63], v[72:73], v[62:63] op_sel_hi:[0,1]
	v_pk_mul_f32 v[52:53], v[72:73], v[52:53] op_sel_hi:[0,1]
	v_pk_mul_f32 v[54:55], v[58:59], v[54:55]
	v_pk_mul_f32 v[60:61], v[64:65], v[60:61]
	v_pk_mul_f32 v[62:63], v[66:67], v[62:63]
	v_pk_mul_f32 v[52:53], v[56:57], v[52:53]
	v_cvt_pk_bf16_f32 v56, v60, v61
	v_cvt_pk_bf16_f32 v57, v62, v63
	v_lshl_add_u64 v[68:69], v[68:69], 0, v[118:119]
	v_cvt_pk_bf16_f32 v58, v52, v53
	v_cvt_pk_bf16_f32 v55, v54, v55
	ds_bpermute_b32 v52, v120, v56
	ds_bpermute_b32 v53, v120, v57
	ds_bpermute_b32 v54, v120, v58
	ds_bpermute_b32 v55, v120, v55
	v_pk_mul_f32 v[16:17], v[12:13], v[16:17]
	v_pk_mul_f32 v[14:15], v[10:11], v[14:15]
	v_pk_mul_f32 v[4:5], v[8:9], v[4:5]
	s_andn2_b64 vcc, exec, s[38:39]
	s_waitcnt lgkmcnt(0)
	global_store_dwordx4 v[68:69], v[52:55], off
	s_nop 1
	v_mov_b32_e32 v55, v241
	s_waitcnt lgkmcnt(0)
	v_mul_f32_e32 v56, v55, v55
	v_mul_f32_e32 v54, 0xbfb8aa3b, v55
	v_pk_mul_f32 v[38:39], v[38:39], v[54:55] op_sel_hi:[1,0]
	v_pk_mul_f32 v[44:45], v[44:45], v[54:55] op_sel_hi:[1,0]
	v_pk_mul_f32 v[46:47], v[46:47], v[54:55] op_sel_hi:[1,0]
	v_pk_mul_f32 v[36:37], v[36:37], v[54:55] op_sel_hi:[1,0]
	v_exp_f32_e32 v38, v38
	v_exp_f32_e32 v39, v39
	v_exp_f32_e32 v44, v44
	v_exp_f32_e32 v45, v45
	v_exp_f32_e32 v46, v46
	v_exp_f32_e32 v47, v47
	v_exp_f32_e32 v36, v36
	v_exp_f32_e32 v37, v37
	v_pk_add_f32 v[38:39], v[38:39], 1.0 op_sel_hi:[1,0]
	v_pk_add_f32 v[44:45], v[44:45], 1.0 op_sel_hi:[1,0]
	v_pk_add_f32 v[46:47], v[46:47], 1.0 op_sel_hi:[1,0]
	v_pk_add_f32 v[36:37], v[36:37], 1.0 op_sel_hi:[1,0]
	v_rcp_f32_e32 v38, v38
	v_rcp_f32_e32 v39, v39
	v_rcp_f32_e32 v44, v44
	v_rcp_f32_e32 v45, v45
	v_rcp_f32_e32 v46, v46
	v_rcp_f32_e32 v47, v47
	v_rcp_f32_e32 v36, v36
	v_rcp_f32_e32 v37, v37
	v_pk_mul_f32 v[38:39], v[56:57], v[38:39] op_sel_hi:[0,1]
	v_pk_mul_f32 v[44:45], v[56:57], v[44:45] op_sel_hi:[0,1]
	v_pk_mul_f32 v[46:47], v[56:57], v[46:47] op_sel_hi:[0,1]
	v_pk_mul_f32 v[36:37], v[56:57], v[36:37] op_sel_hi:[0,1]
	v_pk_mul_f32 v[38:39], v[42:43], v[38:39]
	v_pk_mul_f32 v[44:45], v[48:49], v[44:45]
	v_pk_mul_f32 v[46:47], v[50:51], v[46:47]
	v_pk_mul_f32 v[36:37], v[40:41], v[36:37]
	v_cvt_pk_bf16_f32 v40, v44, v45
	v_cvt_pk_bf16_f32 v41, v46, v47
	v_add_u32_e32 v52, 0x90, v121
	v_cvt_pk_bf16_f32 v42, v36, v37
	v_cvt_pk_bf16_f32 v39, v38, v39
	ds_bpermute_b32 v36, v120, v40
	ds_bpermute_b32 v37, v120, v41
	ds_bpermute_b32 v38, v120, v42
	ds_bpermute_b32 v39, v120, v39
	v_mad_i64_i32 v[52:53], s[8:9], v52, s11, v[116:117]
	v_lshl_add_u64 v[52:53], v[52:53], 0, v[118:119]
	s_waitcnt lgkmcnt(0)
	global_store_dwordx4 v[52:53], v[36:39], off
	s_nop 1
	v_mov_b32_e32 v39, v242
	s_nop 0
	v_add_u32_e32 v36, 0xa0, v121
	v_mad_i64_i32 v[36:37], s[8:9], v36, s11, v[116:117]
	v_lshl_add_u64 v[36:37], v[36:37], 0, v[118:119]
	s_waitcnt lgkmcnt(0)
	v_mul_f32_e32 v38, 0xbfb8aa3b, v39
	v_pk_mul_f32 v[20:21], v[20:21], v[38:39] op_sel_hi:[1,0]
	v_pk_mul_f32 v[26:27], v[26:27], v[38:39] op_sel_hi:[1,0]
	v_pk_mul_f32 v[28:29], v[28:29], v[38:39] op_sel_hi:[1,0]
	v_pk_mul_f32 v[18:19], v[18:19], v[38:39] op_sel_hi:[1,0]
	v_exp_f32_e32 v20, v20
	v_exp_f32_e32 v21, v21
	v_exp_f32_e32 v26, v26
	v_exp_f32_e32 v27, v27
	v_exp_f32_e32 v28, v28
	v_exp_f32_e32 v29, v29
	v_exp_f32_e32 v18, v18
	v_exp_f32_e32 v19, v19
	v_pk_add_f32 v[20:21], v[20:21], 1.0 op_sel_hi:[1,0]
	v_pk_add_f32 v[26:27], v[26:27], 1.0 op_sel_hi:[1,0]
	v_pk_add_f32 v[28:29], v[28:29], 1.0 op_sel_hi:[1,0]
	v_pk_add_f32 v[18:19], v[18:19], 1.0 op_sel_hi:[1,0]
	v_rcp_f32_e32 v20, v20
	v_rcp_f32_e32 v21, v21
	v_rcp_f32_e32 v26, v26
	v_rcp_f32_e32 v27, v27
	v_rcp_f32_e32 v28, v28
	v_rcp_f32_e32 v29, v29
	v_rcp_f32_e32 v18, v18
	v_rcp_f32_e32 v19, v19
	v_mul_f32_e32 v40, v39, v39
	v_pk_mul_f32 v[20:21], v[40:41], v[20:21] op_sel_hi:[0,1]
	v_pk_mul_f32 v[26:27], v[40:41], v[26:27] op_sel_hi:[0,1]
	v_pk_mul_f32 v[28:29], v[40:41], v[28:29] op_sel_hi:[0,1]
	v_pk_mul_f32 v[18:19], v[40:41], v[18:19] op_sel_hi:[0,1]
	v_pk_mul_f32 v[20:21], v[24:25], v[20:21]
	v_pk_mul_f32 v[26:27], v[30:31], v[26:27]
	v_pk_mul_f32 v[28:29], v[32:33], v[28:29]
	v_pk_mul_f32 v[18:19], v[22:23], v[18:19]
	v_cvt_pk_bf16_f32 v22, v26, v27
	v_cvt_pk_bf16_f32 v23, v28, v29
	s_nop 0
	v_cvt_pk_bf16_f32 v24, v18, v19
	v_cvt_pk_bf16_f32 v21, v20, v21
	ds_bpermute_b32 v18, v120, v22
	ds_bpermute_b32 v19, v120, v23
	ds_bpermute_b32 v20, v120, v24
	ds_bpermute_b32 v21, v120, v21
	s_waitcnt lgkmcnt(0)
	global_store_dwordx4 v[36:37], v[18:21], off
	s_nop 1
	v_mov_b32_e32 v21, v243
	s_nop 0
	v_add_u32_e32 v18, 0xb0, v121
	v_mad_i64_i32 v[18:19], s[8:9], v18, s11, v[116:117]
	v_lshl_add_u64 v[18:19], v[18:19], 0, v[118:119]
	s_waitcnt lgkmcnt(0)
	v_mul_f32_e32 v20, 0xbfb8aa3b, v21
	v_pk_mul_f32 v[6:7], v[6:7], v[20:21] op_sel_hi:[1,0]
	v_mul_f32_e32 v22, v21, v21
	v_exp_f32_e32 v6, v6
	v_exp_f32_e32 v7, v7
	v_pk_mul_f32 v[10:11], v[10:11], v[20:21] op_sel_hi:[1,0]
	v_pk_mul_f32 v[12:13], v[12:13], v[20:21] op_sel_hi:[1,0]
	v_exp_f32_e32 v10, v10
	v_pk_add_f32 v[6:7], v[6:7], 1.0 op_sel_hi:[1,0]
	v_exp_f32_e32 v11, v11
	v_rcp_f32_e32 v6, v6
	v_rcp_f32_e32 v7, v7
	v_exp_f32_e32 v12, v12
	v_exp_f32_e32 v13, v13
	v_pk_add_f32 v[10:11], v[10:11], 1.0 op_sel_hi:[1,0]
	v_pk_mul_f32 v[6:7], v[22:23], v[6:7] op_sel_hi:[0,1]
	v_pk_mul_f32 v[2:3], v[2:3], v[6:7]
	v_pk_mul_f32 v[6:7], v[8:9], v[20:21] op_sel_hi:[1,0]
	v_pk_add_f32 v[12:13], v[12:13], 1.0 op_sel_hi:[1,0]
	v_exp_f32_e32 v6, v6
	v_exp_f32_e32 v7, v7
	v_rcp_f32_e32 v10, v10
	v_rcp_f32_e32 v11, v11
	v_rcp_f32_e32 v12, v12
	v_pk_add_f32 v[6:7], v[6:7], 1.0 op_sel_hi:[1,0]
	v_rcp_f32_e32 v13, v13
	v_rcp_f32_e32 v6, v6
	v_rcp_f32_e32 v7, v7
	v_pk_mul_f32 v[10:11], v[22:23], v[10:11] op_sel_hi:[0,1]
	v_pk_mul_f32 v[12:13], v[22:23], v[12:13] op_sel_hi:[0,1]
	v_pk_mul_f32 v[10:11], v[14:15], v[10:11]
	v_pk_mul_f32 v[6:7], v[22:23], v[6:7] op_sel_hi:[0,1]
	v_pk_mul_f32 v[4:5], v[4:5], v[6:7]
	v_pk_mul_f32 v[12:13], v[16:17], v[12:13]
	v_cvt_pk_bf16_f32 v6, v10, v11
	s_mov_b64 s[8:9], -1
	v_cvt_pk_bf16_f32 v7, v12, v13
	v_cvt_pk_bf16_f32 v8, v2, v3
	v_cvt_pk_bf16_f32 v5, v4, v5
	ds_bpermute_b32 v2, v120, v6
	ds_bpermute_b32 v3, v120, v7
	ds_bpermute_b32 v4, v120, v8
	ds_bpermute_b32 v5, v120, v5
	s_waitcnt lgkmcnt(0)
	global_store_dwordx4 v[18:19], v[2:5], off
	s_cbranch_vccnz .LBB0_1110
	s_andn2_b64 vcc, exec, s[4:5]
	s_cbranch_vccnz .LBB0_1109
	s_barrier
	s_branch .LBB0_1109
